# grid barrier: early asynchronous L2 write-back by the 8th-from-last arriver of each XCD, on top of the MFMA order change
# baseline (speedup 1.0000x reference)
; __device__ __forceinline__ unsigned xb_ld(unsigned* p)              { return __hip_atomic_load(p, __ATOMIC_RELAXED, __HIP_MEMORY_SCOPE_AGENT); }
; __device__ __forceinline__ unsigned xb_add(unsigned* p, unsigned v) { return __hip_atomic_fetch_add(p, v, __ATOMIC_RELAXED, __HIP_MEMORY_SCOPE_AGENT); }
; #define XB_SPIN(cond, bar) do { unsigned _sp = 0; while (cond) { __builtin_amdgcn_s_sleep(1); \
;     if ((++_sp & 255u) == 0u) { if (xb_ld(&(bar)[XB_TMO])) break; if (_sp > XB_SPIN_CAP) { atomicAdd(&(bar)[XB_TMO], 1u); break; } } } } while (0)
; __device__ __forceinline__ void xcd_barrier(const XcdBarrier& b) {
;     ...
;         const unsigned old = xb_add(&bar[XB_XSUB(b.x)], 1u);
;         const unsigned gen = old / nloc;
;         if (old + 1u == (gen + 1u) * nloc) {
;             __builtin_amdgcn_fence(__ATOMIC_RELEASE, "agent");
;             asm volatile("s_waitcnt vmcnt(0)" ::: "memory");
;             const unsigned og = xb_add(&bar[XB_TOP], 1u);
;             const unsigned tg = og / nx;
;             if (og + 1u == (tg + 1u) * nx) xb_add(&bar[XB_TOPGEN], 1u);
;             else XB_SPIN(xb_ld(&bar[XB_TOPGEN]) == tg, bar);
;             __builtin_amdgcn_fence(__ATOMIC_ACQUIRE, "agent");
;             xb_add(&bar[XB_XGEN(b.x)], 1u);
;             asm volatile("s_waitcnt vmcnt(0)" ::: "memory");
;         } else {
;             XB_SPIN(xb_ld(&bar[XB_XGEN(b.x)]) == gen, bar);
.LBB0_139:
	s_or_b64 exec, exec, s[6:7]
	v_cvt_f32_u32_e32 v5, v3
	s_waitcnt vmcnt(0)
	v_readfirstlane_b32 s0, v4
	v_sub_u32_e32 v4, 0, v3
	v_rcp_iflag_f32_e32 v5, v5
	v_add_u32_e32 v6, s0, v2
	v_mul_f32_e32 v5, 0x4f7ffffe, v5
	v_cvt_u32_f32_e32 v5, v5
	v_mul_lo_u32 v2, v4, v5
	v_mul_hi_u32 v2, v5, v2
	v_add_u32_e32 v2, v5, v2
	v_mul_hi_u32 v2, v6, v2
	v_mul_lo_u32 v4, v2, v3
	v_sub_u32_e32 v4, v6, v4
	v_add_u32_e32 v5, 1, v2
	v_sub_u32_e32 v7, v4, v3
	v_cmp_ge_u32_e32 vcc, v4, v3
	s_nop 1
	v_cndmask_b32_e32 v2, v2, v5, vcc
	v_cndmask_b32_e32 v4, v4, v7, vcc
	v_add_u32_e32 v5, 1, v2
	v_cmp_ge_u32_e32 vcc, v4, v3
	v_add_u32_e32 v4, 1, v6
	s_nop 0
	v_cndmask_b32_e32 v2, v2, v5, vcc
	v_mul_lo_u32 v5, v3, v2
	v_add_u32_e32 v3, v5, v3
	v_cmp_ne_u32_e32 vcc, v4, v3
	s_and_saveexec_b64 s[0:1], vcc
	s_xor_b64 s[6:7], exec, s[0:1]
	s_cbranch_execz .LBB0_153
	v_add_u32_e32 v5, 8, v4
	v_cmp_eq_u32_e32 vcc, v5, v3
	s_cbranch_vccz .Lnopf_0
	buffer_wbl2 sc1
.Lnopf_0:
	v_readlane_b32 s0, v251, 8
	s_waitcnt lgkmcnt(0)
	v_mov_b32_e32 v1, 0
	v_readlane_b32 s1, v251, 9
	s_nop 4
	global_load_dword v3, v1, s[0:1] sc1
	s_waitcnt vmcnt(0)
	v_cmp_eq_u32_e32 vcc, v3, v2
	s_and_saveexec_b64 s[8:9], vcc
	s_cbranch_execz .LBB0_152
	s_mov_b32 s0, 1
	s_mov_b64 s[10:11], 0
	s_branch .LBB0_143

; __device__ __forceinline__ unsigned xb_ld(unsigned* p)              { return __hip_atomic_load(p, __ATOMIC_RELAXED, __HIP_MEMORY_SCOPE_AGENT); }
; __device__ __forceinline__ unsigned xb_add(unsigned* p, unsigned v) { return __hip_atomic_fetch_add(p, v, __ATOMIC_RELAXED, __HIP_MEMORY_SCOPE_AGENT); }
; #define XB_SPIN(cond, bar) do { unsigned _sp = 0; while (cond) { __builtin_amdgcn_s_sleep(1); \
;     if ((++_sp & 255u) == 0u) { if (xb_ld(&(bar)[XB_TMO])) break; if (_sp > XB_SPIN_CAP) { atomicAdd(&(bar)[XB_TMO], 1u); break; } } } } while (0)
; __device__ __forceinline__ void xcd_barrier(const XcdBarrier& b) {
;     ...
;         const unsigned old = xb_add(&bar[XB_XSUB(b.x)], 1u);
;         const unsigned gen = old / nloc;
;         if (old + 1u == (gen + 1u) * nloc) {
;             __builtin_amdgcn_fence(__ATOMIC_RELEASE, "agent");
;             asm volatile("s_waitcnt vmcnt(0)" ::: "memory");
;             const unsigned og = xb_add(&bar[XB_TOP], 1u);
;             const unsigned tg = og / nx;
;             if (og + 1u == (tg + 1u) * nx) xb_add(&bar[XB_TOPGEN], 1u);
;             else XB_SPIN(xb_ld(&bar[XB_TOPGEN]) == tg, bar);
;             __builtin_amdgcn_fence(__ATOMIC_ACQUIRE, "agent");
;             xb_add(&bar[XB_XGEN(b.x)], 1u);
;             asm volatile("s_waitcnt vmcnt(0)" ::: "memory");
;         } else {
;             XB_SPIN(xb_ld(&bar[XB_XGEN(b.x)]) == gen, bar);
.LBB0_225:
	s_or_b64 exec, exec, s[6:7]
	v_cvt_f32_u32_e32 v5, v3
	s_waitcnt vmcnt(0)
	v_readfirstlane_b32 s0, v4
	v_sub_u32_e32 v4, 0, v3
	v_rcp_iflag_f32_e32 v5, v5
	v_add_u32_e32 v6, s0, v1
	v_mul_f32_e32 v5, 0x4f7ffffe, v5
	v_cvt_u32_f32_e32 v5, v5
	v_mul_lo_u32 v1, v4, v5
	v_mul_hi_u32 v1, v5, v1
	v_add_u32_e32 v1, v5, v1
	v_mul_hi_u32 v1, v6, v1
	v_mul_lo_u32 v4, v1, v3
	v_sub_u32_e32 v4, v6, v4
	v_add_u32_e32 v5, 1, v1
	v_cmp_ge_u32_e32 vcc, v4, v3
	s_nop 1
	v_cndmask_b32_e32 v1, v1, v5, vcc
	v_sub_u32_e32 v5, v4, v3
	v_cndmask_b32_e32 v4, v4, v5, vcc
	v_add_u32_e32 v5, 1, v1
	v_cmp_ge_u32_e32 vcc, v4, v3
	v_add_u32_e32 v4, 1, v6
	s_nop 0
	v_cndmask_b32_e32 v1, v1, v5, vcc
	v_mul_lo_u32 v5, v3, v1
	v_add_u32_e32 v3, v5, v3
	v_cmp_ne_u32_e32 vcc, v4, v3
	s_and_saveexec_b64 s[0:1], vcc
	s_xor_b64 s[6:7], exec, s[0:1]
	s_cbranch_execz .LBB0_239
	v_add_u32_e32 v5, 8, v4
	v_cmp_eq_u32_e32 vcc, v5, v3
	s_cbranch_vccz .Lnopf_1
	buffer_wbl2 sc1
.Lnopf_1:
	v_readlane_b32 s0, v251, 8
	v_readlane_b32 s1, v251, 9
	s_waitcnt lgkmcnt(0)
	s_nop 3
	global_load_dword v2, v98, s[0:1] sc1
	s_waitcnt vmcnt(0)
	v_cmp_eq_u32_e32 vcc, v2, v1
	s_and_saveexec_b64 s[8:9], vcc
	s_cbranch_execz .LBB0_238
	s_mov_b32 s0, 1
	s_mov_b64 s[10:11], 0
	s_branch .LBB0_229
